# tile order: FFN-down GEMMs cover 4 row panels x all 8 column tiles per XCD step (was 8 x 4), so each hid row panel is streamed from HBM once per phase and shared by 8 workgroups
# speedup vs baseline: 1.0117x; 1.0117x over previous
;     __host__ __device__ __forceinline__ bool next(int i, Unit& u) const {
;         const long L = (long)i * G + c; if (L >= nwg) return false;
;         int wgid = (int)L; { const int q = nwg / NXCD, r = nwg % NXCD, xcd = wgid % NXCD, off = wgid / NXCD; wgid = (xcd < r ? xcd * (q + 1) : r * (q + 1) + (xcd - r) * q) + off; }
;         const int nig = WGM * nN, gid = wgid / nig, fm = gid * WGM, gsz = (nM - fm) < WGM ? (nM - fm) : WGM;
;         u.pm = fm + ((wgid % nig) % gsz); u.pn = (wgid % nig) / gsz; return true;
;     }
.LBB0_230:
	s_ashr_i32 s6, s8, 3
	s_add_i32 s6, s11, s6
	s_ashr_i32 s7, s6, 31
	s_lshr_b32 s7, s7, 26
	s_add_i32 s7, s6, s7
	s_ashr_i32 s8, s7, 6
	s_and_b32 s7, s7, 0xffc0
	s_sub_i32 s6, s6, s7
	s_bfe_i32 s7, s6, 0x80000
	s_bfe_u32 s7, s7, 0x3000c
	s_add_i32 s7, s6, s7
	s_bfe_i32 s9, s7, 0x80000
	s_and_b32 s7, s7, 0xf8
	s_sub_i32 s6, s6, s7
	s_lshl_b32 s8, s8, 3
	s_sext_i32_i16 s9, s9
	s_sext_i32_i8 s6, s6
	s_add_i32 s52, s8, s6
	s_ashr_i32 s51, s9, 3
	s_lshr_b32 s6, s51, 2
	s_lshl_b32 s6, s6, 2
	s_and_b32 s7, s52, 3
	s_add_i32 s6, s6, s7
	s_bfe_u32 s7, s52, 0x10002
	s_and_b32 s51, s51, 3
	s_lshl_b32 s51, s51, 1
	s_add_i32 s51, s51, s7
	s_and_b32 s52, s52, -8
	s_add_i32 s52, s52, s6

;     __host__ __device__ __forceinline__ bool next(int i, Unit& u) const {
;         const long L = (long)i * G + c; if (L >= nwg) return false;
;         int wgid = (int)L; { const int q = nwg / NXCD, r = nwg % NXCD, xcd = wgid % NXCD, off = wgid / NXCD; wgid = (xcd < r ? xcd * (q + 1) : r * (q + 1) + (xcd - r) * q) + off; }
;         const int nig = WGM * nN, gid = wgid / nig, fm = gid * WGM, gsz = (nM - fm) < WGM ? (nM - fm) : WGM;
;         u.pm = fm + ((wgid % nig) % gsz); u.pn = (wgid % nig) / gsz; return true;
;     }
;     ...
;         const bool has_next = S.next(ui + 1, nxt);
.LBB0_242:
	s_ashr_i32 s4, s20, 3
	s_add_i32 s4, s22, s4
	s_ashr_i32 s5, s4, 31
	s_lshr_b32 s5, s5, 26
	s_add_i32 s5, s4, s5
	s_ashr_i32 s20, s5, 6
	s_lshl_b32 s20, s20, 3
	s_sub_i32 s21, 64, s20
	s_min_i32 s21, s21, 8
	s_abs_i32 s22, s21
	v_cvt_f32_u32_e32 v2, s22
	s_sub_i32 s26, 0, s22
	s_andn2_b32 s5, s5, 63
	s_sub_i32 s4, s4, s5
	v_rcp_iflag_f32_e32 v2, v2
	s_abs_i32 s5, s4
	s_xor_b32 s23, s4, s21
	s_ashr_i32 s23, s23, 31
	v_mul_f32_e32 v2, 0x4f7ffffe, v2
	v_cvt_u32_f32_e32 v2, v2
	s_nop 0
	v_readfirstlane_b32 s27, v2
	s_mul_i32 s26, s26, s27
	s_mul_hi_u32 s26, s27, s26
	s_add_i32 s27, s27, s26
	s_mul_hi_u32 s26, s5, s27
	s_mul_i32 s27, s26, s22
	s_sub_i32 s5, s5, s27
	s_add_i32 s49, s26, 1
	s_sub_i32 s27, s5, s22
	s_cmp_ge_u32 s5, s22
	s_cselect_b32 s26, s49, s26
	s_cselect_b32 s5, s27, s5
	s_add_i32 s27, s26, 1
	s_cmp_ge_u32 s5, s22
	s_cselect_b32 s5, s27, s26
	s_xor_b32 s5, s5, s23
	s_sub_i32 s49, s5, s23
	s_mul_i32 s5, s49, s21
	s_sub_i32 s4, s4, s5
	s_add_i32 s50, s20, s4
	s_lshr_b32 s4, s49, 2
	s_lshl_b32 s4, s4, 2
	s_and_b32 s5, s50, 3
	s_add_i32 s4, s4, s5
	s_bfe_u32 s5, s50, 0x10002
	s_and_b32 s49, s49, 3
	s_lshl_b32 s49, s49, 1
	s_add_i32 s49, s49, s5
	s_and_b32 s50, s50, -8
	s_add_i32 s50, s50, s4

;     __host__ __device__ __forceinline__ bool next(int i, Unit& u) const {
;         const long L = (long)i * G + c; if (L >= nwg) return false;
;         int wgid = (int)L; { const int q = nwg / NXCD, r = nwg % NXCD, xcd = wgid % NXCD, off = wgid / NXCD; wgid = (xcd < r ? xcd * (q + 1) : r * (q + 1) + (xcd - r) * q) + off; }
;         const int nig = WGM * nN, gid = wgid / nig, fm = gid * WGM, gsz = (nM - fm) < WGM ? (nM - fm) : WGM;
;         u.pm = fm + ((wgid % nig) % gsz); u.pn = (wgid % nig) / gsz; return true;
;     }
.LBB0_1206:
	s_ashr_i32 s6, s9, 3
	s_add_i32 s6, s11, s6
	s_ashr_i32 s7, s6, 31
	s_lshr_b32 s7, s7, 26
	s_add_i32 s7, s6, s7
	s_ashr_i32 s9, s7, 6
	s_and_b32 s7, s7, 0xffc0
	s_sub_i32 s6, s6, s7
	s_bfe_i32 s7, s6, 0x80000
	s_bfe_u32 s7, s7, 0x3000c
	s_add_i32 s7, s6, s7
	s_bfe_i32 s10, s7, 0x80000
	s_and_b32 s7, s7, 0xf8
	s_sub_i32 s6, s6, s7
	s_lshl_b32 s9, s9, 3
	s_sext_i32_i16 s10, s10
	s_sext_i32_i8 s6, s6
	s_add_i32 s48, s9, s6
	s_ashr_i32 s47, s10, 3
	s_lshr_b32 s6, s47, 2
	s_lshl_b32 s6, s6, 2
	s_and_b32 s7, s48, 3
	s_add_i32 s6, s6, s7
	s_bfe_u32 s7, s48, 0x10002
	s_and_b32 s47, s47, 3
	s_lshl_b32 s47, s47, 1
	s_add_i32 s47, s47, s7
	s_and_b32 s48, s48, -8
	s_add_i32 s48, s48, s6

;     __host__ __device__ __forceinline__ bool next(int i, Unit& u) const {
;         const long L = (long)i * G + c; if (L >= nwg) return false;
;         int wgid = (int)L; { const int q = nwg / NXCD, r = nwg % NXCD, xcd = wgid % NXCD, off = wgid / NXCD; wgid = (xcd < r ? xcd * (q + 1) : r * (q + 1) + (xcd - r) * q) + off; }
;         const int nig = WGM * nN, gid = wgid / nig, fm = gid * WGM, gsz = (nM - fm) < WGM ? (nM - fm) : WGM;
;         u.pm = fm + ((wgid % nig) % gsz); u.pn = (wgid % nig) / gsz; return true;
;     }
;     ...
;         const bool has_next = S.next(ui + 1, nxt);
.LBB0_1218:
	s_ashr_i32 s4, s14, 3
	s_add_i32 s4, s16, s4
	s_ashr_i32 s5, s4, 31
	s_lshr_b32 s5, s5, 26
	s_add_i32 s5, s4, s5
	s_ashr_i32 s14, s5, 6
	s_lshl_b32 s14, s14, 3
	s_sub_i32 s15, 64, s14
	s_min_i32 s15, s15, 8
	s_abs_i32 s16, s15
	v_cvt_f32_u32_e32 v2, s16
	s_sub_i32 s22, 0, s16
	s_andn2_b32 s5, s5, 63
	s_sub_i32 s4, s4, s5
	v_rcp_iflag_f32_e32 v2, v2
	s_abs_i32 s5, s4
	s_xor_b32 s17, s4, s15
	s_ashr_i32 s17, s17, 31
	v_mul_f32_e32 v2, 0x4f7ffffe, v2
	v_cvt_u32_f32_e32 v2, v2
	s_nop 0
	v_readfirstlane_b32 s23, v2
	s_mul_i32 s22, s22, s23
	s_mul_hi_u32 s22, s23, s22
	s_add_i32 s23, s23, s22
	s_mul_hi_u32 s22, s5, s23
	s_mul_i32 s23, s22, s16
	s_sub_i32 s5, s5, s23
	s_add_i32 s45, s22, 1
	s_sub_i32 s23, s5, s16
	s_cmp_ge_u32 s5, s16
	s_cselect_b32 s22, s45, s22
	s_cselect_b32 s5, s23, s5
	s_add_i32 s23, s22, 1
	s_cmp_ge_u32 s5, s16
	s_cselect_b32 s5, s23, s22
	s_xor_b32 s5, s5, s17
	s_sub_i32 s45, s5, s17
	s_mul_i32 s5, s45, s15
	s_sub_i32 s4, s4, s5
	s_add_i32 s46, s14, s4
	s_lshr_b32 s4, s45, 2
	s_lshl_b32 s4, s4, 2
	s_and_b32 s5, s46, 3
	s_add_i32 s4, s4, s5
	s_bfe_u32 s5, s46, 0x10002
	s_and_b32 s45, s45, 3
	s_lshl_b32 s45, s45, 1
	s_add_i32 s45, s45, s5
	s_and_b32 s46, s46, -8
	s_add_i32 s46, s46, s4
